# prologue weight transpose loop rewritten by hand: 16-byte source loads, gain vector loaded once per item (14 VMEM per item instead of 68)
# speedup vs baseline: 1.0260x; 1.0190x over previous
.LBB0_505:
	s_andn2_b64 vcc, exec, s[26:27]
	s_cbranch_vccnz .LBB0_675
	v_readlane_b32 s2, v252, 10
	v_mbcnt_lo_u32_b32 v0, -1, 0
	v_mbcnt_hi_u32_b32 v0, -1, v0
	s_nop 0
	v_and_b32_e32 v9, 63, v0
	s_waitcnt vmcnt(17)
	v_add_u32_e32 v58, s2, v0
	s_nop 0
	v_readfirstlane_b32 s2, v58
	s_ashr_i32 s3, s2, 6
	v_readlane_b32 s2, v252, 27
	s_add_i32 s2, s3, s2
	s_cmpk_gt_i32 s2, 0x47ff
	s_cbranch_scc1 .LBB0_660
	v_lshrrev_b32_e32 v6, 5, v9
	v_and_b32_e32 v8, 31, v0
	v_mov_b32_e32 v0, 0x108
	s_movk_i32 s17, 0x84
	v_mad_u32_u24 v16, v6, s17, v0
	v_mov_b32_e32 v0, 0x210
	v_mad_u32_u24 v18, v6, s17, v0
	v_mov_b32_e32 v0, 0x318
	v_mad_u32_u24 v20, v6, s17, v0
	v_mov_b32_e32 v0, 0x420
	v_mad_u32_u24 v22, v6, s17, v0
	v_mov_b32_e32 v0, 0x528
	v_mad_u32_u24 v24, v6, s17, v0
	v_mov_b32_e32 v0, 0x630
	v_mad_u32_u24 v26, v6, s17, v0
	v_mov_b32_e32 v0, 0x738
	v_mad_u32_u24 v28, v6, s17, v0
	v_mov_b32_e32 v0, 0x840
	v_mad_u32_u24 v30, v6, s17, v0
	v_mov_b32_e32 v0, 0x948
	v_mad_u32_u24 v32, v6, s17, v0
	v_mov_b32_e32 v0, 0xa50
	v_mad_u32_u24 v34, v6, s17, v0
	v_mov_b32_e32 v0, 0xb58
	v_mad_u32_u24 v36, v6, s17, v0
	v_lshlrev_b32_e32 v0, 3, v9
	s_lshl_b32 s3, s3, 14
	v_lshrrev_b32_e32 v37, 3, v9
	v_and_b32_e32 v10, 56, v0
	s_add_i32 s3, s3, 0
	v_mul_u32_u24_e32 v0, 0x84, v10
	s_waitcnt lgkmcnt(0)
	v_lshlrev_b32_e32 v2, 2, v37
	v_add3_u32 v38, s3, v0, v2
	v_mov_b32_e32 v0, 0xc60
	v_readlane_b32 s10, v255, 4
	v_mad_u32_u24 v40, v6, s17, v0
	v_mov_b32_e32 v0, 0xd68
	v_readlane_b32 s11, v255, 5
	s_mov_b32 s16, s10
	v_mad_u32_u24 v42, v6, s17, v0
	v_mov_b32_e32 v0, 0xf78
	v_lshl_add_u32 v11, v8, 2, s3
	v_mul_u32_u24_e32 v14, 0x84, v6
	v_or_b32_e32 v15, 2, v6
	v_or_b32_e32 v17, 4, v6
	v_or_b32_e32 v19, 6, v6
	v_or_b32_e32 v21, 8, v6
	v_or_b32_e32 v23, 10, v6
	v_or_b32_e32 v25, 12, v6
	v_or_b32_e32 v27, 14, v6
	v_or_b32_e32 v29, 16, v6
	v_or_b32_e32 v31, 18, v6
	v_or_b32_e32 v33, 20, v6
	v_or_b32_e32 v35, 22, v6
	v_or_b32_e32 v39, 24, v6
	v_mov_b32_e32 v7, v1
	s_lshl_b32 s3, s2, 1
	s_lshl_b32 s6, s10, 1
	s_lshl_b32 s10, s2, 5
	s_lshl_b32 s11, s16, 5
	s_mov_b32 s16, s2
	v_or_b32_e32 v41, 26, v6
	v_or_b32_e32 v43, 28, v6
	v_mad_u32_u24 v44, v6, s17, v251
	v_or_b32_e32 v45, 30, v6
	v_mad_u32_u24 v46, v6, s17, v0
	v_or_b32_e32 v47, 32, v6
	v_mad_u32_u24 v48, v6, s17, v226
	v_or_b32_e32 v49, 34, v6
	v_mad_u32_u24 v50, v6, s17, v227
	v_or_b32_e32 v51, 36, v6
	v_mad_u32_u24 v52, v6, s17, v228
	v_or_b32_e32 v53, 38, v6
	v_or_b32_e32 v54, 40, v6
	v_or_b32_e32 v55, 42, v6
	v_or_b32_e32 v56, 44, v6
	v_or_b32_e32 v57, 46, v6
	v_or_b32_e32 v59, 48, v6
	v_or_b32_e32 v60, 50, v6
	v_or_b32_e32 v61, 52, v6
	s_waitcnt vmcnt(16)
	v_or_b32_e32 v62, 54, v6
	v_or_b32_e32 v63, 56, v6
	v_or_b32_e32 v64, 58, v6
	v_or_b32_e32 v65, 60, v6
	s_waitcnt vmcnt(15)
	v_or_b32_e32 v66, 62, v6
	v_or_b32_e32 v67, 8, v37
	v_or_b32_e32 v68, 16, v37
	v_or_b32_e32 v69, 24, v37
	v_readlane_b32 s16, v252, 4
	v_readlane_b32 s17, v252, 5
	v_readlane_b32 s75, v255, 4
	v_readfirstlane_b32 s3, v58
	s_nop 3
	s_add_u32 s16, s16, 0xffffff58
	s_addc_u32 s17, s17, -1
	s_load_dwordx4 s[60:63], s[16:17], 0x10
	s_load_dwordx4 s[64:67], s[16:17], 0x48
	s_load_dwordx2 s[68:69], s[16:17], 0x58
	s_load_dwordx2 s[70:71], s[16:17], 0x78
	s_add_u32 s72, s8, 0x800000
	s_addc_u32 s73, s9, 0
	s_mov_b32 s74, s2
	s_lshr_b32 s3, s3, 6
	s_lshl_b32 s3, s3, 14
	v_lshrrev_b32_e32 v10, 3, v9
	v_and_b32_e32 v2, 7, v9
	v_lshlrev_b32_e32 v11, 4, v2
	v_lshlrev_b32_e32 v12, 5, v2
	v_mul_u32_u24_e32 v3, 33, v10
	v_lshl_add_u32 v3, v2, 2, v3
	v_lshl_add_u32 v13, v3, 2, s3
	v_mul_u32_u24_e32 v3, 0x108, v2
	v_add_u32_e32 v3, v3, v10
	v_lshl_add_u32 v14, v3, 2, s3
	s_waitcnt lgkmcnt(0)
.Ltr_loop:
	s_cmpk_ge_u32 s74, 0x2400
	s_cselect_b32 s18, 1, 0
	s_mul_i32 s19, s18, 0x2400
	s_sub_u32 s19, s74, s19
	s_cmpk_lt_u32 s19, 0x1000
	s_cbranch_scc1 .Ltr_A
	s_cmpk_lt_u32 s19, 0x1400
	s_cbranch_scc1 .Ltr_B
	s_cmpk_lt_u32 s19, 0x2000
	s_cbranch_scc1 .Ltr_C
	s_sub_u32 s19, s19, 0x2000
	s_mov_b64 s[26:27], s[70:71]
	s_mov_b32 s10, 0x4000000
	s_branch .Ltr_BD
.Ltr_B:
	s_sub_u32 s19, s19, 0x1000
	s_mov_b64 s[26:27], s[64:65]
	s_mov_b32 s10, 0x2000000
.Ltr_BD:
	s_lshr_b32 s20, s19, 5
	s_and_b32 s21, s19, 31
	s_lshl_b32 s21, s21, 5
	s_movk_i32 s38, 0x1000
	s_movk_i32 s44, 0x1000
	s_lshl_b32 s22, s18, 23
	s_lshl_b32 s23, s20, 18
	s_add_u32 s22, s22, s23
	s_lshl_b32 s23, s21, 2
	s_add_u32 s22, s22, s23
	s_add_u32 s36, s26, s22
	s_addc_u32 s37, s27, 0
	s_mov_b32 s39, 0
	s_lshl_b32 s22, s18, 22
	s_add_u32 s22, s22, s10
	s_lshl_b32 s23, s21, 12
	s_add_u32 s22, s22, s23
	s_lshl_b32 s23, s20, 7
	s_add_u32 s22, s22, s23
	s_add_u32 s42, s72, s22
	s_addc_u32 s43, s73, 0
	s_branch .Ltr_go
.Ltr_A:
	s_lshr_b32 s20, s19, 8
	s_and_b32 s21, s19, 0xff
	s_lshl_b32 s21, s21, 5
	s_add_u32 s22, s21, 0x800
	s_sub_u32 s23, s21, 0x800
	s_cmpk_lt_u32 s21, 0x1800
	s_cselect_b32 s22, s22, s23
	s_cmpk_lt_u32 s21, 0x1000
	s_cselect_b32 s22, s21, s22
	s_mov_b32 s38, 0x8000
	s_movk_i32 s44, 0x800
	s_lshl_b32 s26, s18, 25
	s_lshl_b32 s27, s20, 21
	s_add_u32 s26, s26, s27
	s_lshl_b32 s27, s21, 2
	s_add_u32 s26, s26, s27
	s_add_u32 s36, s62, s26
	s_addc_u32 s37, s63, 0
	s_lshl_b32 s26, s18, 12
	s_lshl_b32 s27, s20, 8
	s_add_u32 s26, s26, s27
	s_add_u32 s40, s60, s26
	s_addc_u32 s41, s61, 0
	s_mov_b32 s39, 1
	s_lshl_b32 s26, s18, 24
	s_lshl_b32 s27, s22, 11
	s_add_u32 s26, s26, s27
	s_lshl_b32 s27, s20, 7
	s_add_u32 s26, s26, s27
	s_add_u32 s42, s72, s26
	s_addc_u32 s43, s73, 0
	s_branch .Ltr_go
.Ltr_C:
	s_sub_u32 s19, s19, 0x1400
	s_mul_hi_u32 s20, s19, 0x1555556
	s_mul_i32 s21, s20, 0xc0
	s_sub_u32 s21, s19, s21
	s_lshl_b32 s21, s21, 5
	s_sub_u32 s23, s21, 0x1000
	s_cmpk_lt_u32 s21, 0x800
	s_cselect_b32 s23, s21, s23
	s_lshr_b32 s22, s23, 7
	s_lshl_b32 s22, s22, 8
	s_and_b32 s23, s23, 0x7f
	s_add_u32 s22, s22, s23
	s_add_u32 s23, s22, 0x80
	s_cmpk_lt_u32 s21, 0x800
	s_cselect_b32 s22, s22, s23
	s_add_u32 s23, s21, 0x800
	s_cmpk_lt_u32 s21, 0x800
	s_cselect_b32 s26, 1, 0
	s_cmpk_ge_u32 s21, 0x1000
	s_cselect_b32 s27, 1, 0
	s_or_b32 s26, s26, s27
	s_cmp_lg_u32 s26, 0
	s_cselect_b32 s22, s22, s23
	s_mov_b32 s38, 0x6000
	s_movk_i32 s44, 0x800
	s_mul_i32 s26, s18, 0x1800000
	s_mul_i32 s27, s20, 0x180000
	s_add_u32 s26, s26, s27
	s_lshl_b32 s27, s21, 2
	s_add_u32 s26, s26, s27
	s_add_u32 s36, s68, s26
	s_addc_u32 s37, s69, 0
	s_lshl_b32 s26, s18, 12
	s_lshl_b32 s27, s20, 8
	s_add_u32 s26, s26, s27
	s_add_u32 s40, s66, s26
	s_addc_u32 s41, s67, 0
	s_mov_b32 s39, 1
	s_mul_i32 s26, s18, 0xc00000
	s_add_u32 s26, s26, 0x2800000
	s_lshl_b32 s27, s22, 11
	s_add_u32 s26, s26, s27
	s_lshl_b32 s27, s20, 7
	s_add_u32 s26, s26, s27
	s_add_u32 s42, s72, s26
	s_addc_u32 s43, s73, 0
.Ltr_go:
	v_mad_u32_u24 v15, v10, s38, v11
	v_mad_u32_u24 v16, v10, s44, v11
	s_lshl_b32 s45, s38, 3
	s_cmp_eq_u32 s39, 0
	s_cbranch_scc1 .Ltr_nogain
	global_load_dwordx4 v[52:55], v12, s[40:41]
	global_load_dwordx4 v[60:63], v12, s[40:41] offset:16
	s_branch .Ltr_ld
.Ltr_nogain:
	v_mov_b32_e32 v52, 1.0
	v_mov_b32_e32 v53, 1.0
	v_mov_b32_e32 v54, 1.0
	v_mov_b32_e32 v55, 1.0
	v_mov_b32_e32 v60, 1.0
	v_mov_b32_e32 v61, 1.0
	v_mov_b32_e32 v62, 1.0
	v_mov_b32_e32 v63, 1.0
.Ltr_ld:
	global_load_dwordx4 v[20:23], v15, s[36:37]
	s_add_u32 s36, s36, s45
	s_addc_u32 s37, s37, 0
	global_load_dwordx4 v[24:27], v15, s[36:37]
	s_add_u32 s36, s36, s45
	s_addc_u32 s37, s37, 0
	global_load_dwordx4 v[28:31], v15, s[36:37]
	s_add_u32 s36, s36, s45
	s_addc_u32 s37, s37, 0
	global_load_dwordx4 v[32:35], v15, s[36:37]
	s_add_u32 s36, s36, s45
	s_addc_u32 s37, s37, 0
	global_load_dwordx4 v[36:39], v15, s[36:37]
	s_add_u32 s36, s36, s45
	s_addc_u32 s37, s37, 0
	global_load_dwordx4 v[40:43], v15, s[36:37]
	s_add_u32 s36, s36, s45
	s_addc_u32 s37, s37, 0
	global_load_dwordx4 v[44:47], v15, s[36:37]
	s_add_u32 s36, s36, s45
	s_addc_u32 s37, s37, 0
	global_load_dwordx4 v[48:51], v15, s[36:37]
	s_lshl_b32 s45, s44, 3
	s_waitcnt vmcnt(7)
	ds_write_b32 v13, v20
	ds_write_b32 v13, v21 offset:4
	ds_write_b32 v13, v22 offset:8
	ds_write_b32 v13, v23 offset:12
	s_waitcnt vmcnt(6)
	ds_write_b32 v13, v24 offset:1056
	ds_write_b32 v13, v25 offset:1060
	ds_write_b32 v13, v26 offset:1064
	ds_write_b32 v13, v27 offset:1068
	s_waitcnt vmcnt(5)
	ds_write_b32 v13, v28 offset:2112
	ds_write_b32 v13, v29 offset:2116
	ds_write_b32 v13, v30 offset:2120
	ds_write_b32 v13, v31 offset:2124
	s_waitcnt vmcnt(4)
	ds_write_b32 v13, v32 offset:3168
	ds_write_b32 v13, v33 offset:3172
	ds_write_b32 v13, v34 offset:3176
	ds_write_b32 v13, v35 offset:3180
	s_waitcnt vmcnt(3)
	ds_write_b32 v13, v36 offset:4224
	ds_write_b32 v13, v37 offset:4228
	ds_write_b32 v13, v38 offset:4232
	ds_write_b32 v13, v39 offset:4236
	s_waitcnt vmcnt(2)
	ds_write_b32 v13, v40 offset:5280
	ds_write_b32 v13, v41 offset:5284
	ds_write_b32 v13, v42 offset:5288
	ds_write_b32 v13, v43 offset:5292
	s_waitcnt vmcnt(1)
	ds_write_b32 v13, v44 offset:6336
	ds_write_b32 v13, v45 offset:6340
	ds_write_b32 v13, v46 offset:6344
	ds_write_b32 v13, v47 offset:6348
	s_waitcnt vmcnt(0)
	ds_write_b32 v13, v48 offset:7392
	ds_write_b32 v13, v49 offset:7396
	ds_write_b32 v13, v50 offset:7400
	ds_write_b32 v13, v51 offset:7404
	ds_read2_b32 v[64:65], v14 offset0:0 offset1:33
	ds_read2_b32 v[66:67], v14 offset0:66 offset1:99
	ds_read2_b32 v[68:69], v14 offset0:132 offset1:165
	ds_read2_b32 v[70:71], v14 offset0:198 offset1:231
	ds_read2_b32 v[76:77], v14 offset0:8 offset1:41
	ds_read2_b32 v[78:79], v14 offset0:74 offset1:107
	ds_read2_b32 v[80:81], v14 offset0:140 offset1:173
	ds_read2_b32 v[82:83], v14 offset0:206 offset1:239
	ds_read2_b32 v[84:85], v14 offset0:16 offset1:49
	ds_read2_b32 v[86:87], v14 offset0:82 offset1:115
	ds_read2_b32 v[88:89], v14 offset0:148 offset1:181
	ds_read2_b32 v[90:91], v14 offset0:214 offset1:247
	ds_read2_b32 v[92:93], v14 offset0:24 offset1:57
	ds_read2_b32 v[94:95], v14 offset0:90 offset1:123
	ds_read2_b32 v[96:97], v14 offset0:156 offset1:189
	ds_read2_b32 v[98:99], v14 offset0:222 offset1:255
	s_waitcnt lgkmcnt(12)
	v_pk_mul_f32 v[64:65], v[64:65], v[52:53]
	v_pk_mul_f32 v[66:67], v[66:67], v[54:55]
	v_pk_mul_f32 v[68:69], v[68:69], v[60:61]
	v_pk_mul_f32 v[70:71], v[70:71], v[62:63]
	v_cvt_pk_bf16_f32 v72, v64, v65
	v_cvt_pk_bf16_f32 v73, v66, v67
	v_cvt_pk_bf16_f32 v74, v68, v69
	v_cvt_pk_bf16_f32 v75, v70, v71
	global_store_dwordx4 v16, v[72:75], s[42:43]
	s_add_u32 s42, s42, s45
	s_addc_u32 s43, s43, 0
	s_waitcnt lgkmcnt(8)
	v_pk_mul_f32 v[76:77], v[76:77], v[52:53]
	v_pk_mul_f32 v[78:79], v[78:79], v[54:55]
	v_pk_mul_f32 v[80:81], v[80:81], v[60:61]
	v_pk_mul_f32 v[82:83], v[82:83], v[62:63]
	v_cvt_pk_bf16_f32 v100, v76, v77
	v_cvt_pk_bf16_f32 v101, v78, v79
	v_cvt_pk_bf16_f32 v102, v80, v81
	v_cvt_pk_bf16_f32 v103, v82, v83
	global_store_dwordx4 v16, v[100:103], s[42:43]
	s_add_u32 s42, s42, s45
	s_addc_u32 s43, s43, 0
	s_waitcnt lgkmcnt(4)
	v_pk_mul_f32 v[84:85], v[84:85], v[52:53]
	v_pk_mul_f32 v[86:87], v[86:87], v[54:55]
	v_pk_mul_f32 v[88:89], v[88:89], v[60:61]
	v_pk_mul_f32 v[90:91], v[90:91], v[62:63]
	v_cvt_pk_bf16_f32 v72, v84, v85
	v_cvt_pk_bf16_f32 v73, v86, v87
	v_cvt_pk_bf16_f32 v74, v88, v89
	v_cvt_pk_bf16_f32 v75, v90, v91
	global_store_dwordx4 v16, v[72:75], s[42:43]
	s_add_u32 s42, s42, s45
	s_addc_u32 s43, s43, 0
	s_waitcnt lgkmcnt(0)
	v_pk_mul_f32 v[92:93], v[92:93], v[52:53]
	v_pk_mul_f32 v[94:95], v[94:95], v[54:55]
	v_pk_mul_f32 v[96:97], v[96:97], v[60:61]
	v_pk_mul_f32 v[98:99], v[98:99], v[62:63]
	v_cvt_pk_bf16_f32 v100, v92, v93
	v_cvt_pk_bf16_f32 v101, v94, v95
	v_cvt_pk_bf16_f32 v102, v96, v97
	v_cvt_pk_bf16_f32 v103, v98, v99
	global_store_dwordx4 v16, v[100:103], s[42:43]
	s_add_u32 s74, s74, s75
	s_cmpk_lt_u32 s74, 0x4800
	s_cbranch_scc1 .Ltr_loop
